# v16 plus attention half-step-1 softmax fma/exp block issued before the B1 barrier (RESC temps renamed)
# baseline (speedup 1.0000x reference)
; __device__ __forceinline__ void partialSM(f32x16& p0, f32x16& p1, float& m_reg, float& mn, float& alpha) {
;     float pmax = p0[0];
; #pragma unroll
;     for (int r = 1; r < 16; ++r) pmax = fmaxf(pmax, p0[r]);
; #pragma unroll
;     for (int r = 0; r < 16; ++r) pmax = fmaxf(pmax, p1[r]);
;     { auto rr = __builtin_amdgcn_permlane32_swap(__float_as_uint(pmax), __float_as_uint(pmax), false, false);
;       pmax = fmaxf(__uint_as_float(rr[0]), __uint_as_float(rr[1])); }
;     constexpr float C2 = 1.4426950408889634f * SCALE;
;     if (__builtin_expect(__all((pmax - m_reg) * SCALE <= THR), 1)) { mn = m_reg; alpha = 1.f; }
;     else { mn = fmaxf(m_reg, pmax); alpha = __builtin_amdgcn_exp2f((m_reg - mn) * C2); m_reg = mn; }
;     const float mnL = -mn * C2;
; #pragma unroll
;     for (int r = 0; r < 16; ++r) p0[r] = fmaf(p0[r], C2, mnL);
; #pragma unroll
;     for (int r = 0; r < 16; ++r) p1[r] = fmaf(p1[r], C2, mnL);
; #pragma unroll
;     for (int r = 0; r < 16; ++r) p0[r] = __builtin_amdgcn_exp2f(p0[r]);
; }
.LBB0_973:
	v_max_f32_e32 v149, v81, v81
	v_max_f32_e32 v150, v80, v80
	v_max_f32_e32 v149, v150, v149
	v_max3_f32 v149, v149, v82, v83
	v_max3_f32 v149, v149, v84, v85
	v_max3_f32 v149, v149, v86, v87
	v_max3_f32 v149, v149, v88, v89
	v_max3_f32 v149, v149, v90, v91
	v_max3_f32 v149, v149, v92, v93
	v_max3_f32 v149, v149, v94, v95
	v_max3_f32 v149, v149, v64, v65
	v_max3_f32 v149, v149, v66, v67
	v_max3_f32 v149, v149, v68, v69
	v_max3_f32 v149, v149, v70, v71
	v_max3_f32 v149, v149, v72, v73
	v_max3_f32 v149, v149, v74, v75
	v_max3_f32 v149, v149, v76, v77
	v_max3_f32 v149, v149, v78, v79
	v_mov_b32_e32 v150, v149
	s_nop 1
	v_permlane32_swap_b32_e32 v149, v150
	v_max_f32_e32 v150, v150, v150
	v_max_f32_e32 v149, v149, v149
	v_max_f32_e32 v149, v149, v150
	v_max_f32_e32 v151, v148, v148
	v_sub_f32_e32 v150, v149, v148
	v_max_f32_e32 v149, v151, v149
	v_sub_f32_e32 v151, v148, v149
	v_mul_f32_e32 v151, 0x3dd53b94, v151
	v_mul_f32_e32 v150, 0x3d93cd3a, v150
	v_exp_f32_e32 v151, v151
	v_cmp_ge_f32_e32 vcc, s33, v150
	s_cmp_eq_u64 vcc, exec
	s_cselect_b64 s[6:7], -1, 0
	v_cndmask_b32_e64 v213, v151, 1.0, s[6:7]
	v_cmp_gt_f32_e32 vcc, 1.0, v213
	v_cndmask_b32_e64 v214, v149, v148, s[6:7]
	v_mul_f32_e32 v215, 0xbdd53b94, v214
	v_fmamk_f32 v80, v80, 0x3dd53b94, v215
	v_fmamk_f32 v81, v81, 0x3dd53b94, v215
	v_fmamk_f32 v82, v82, 0x3dd53b94, v215
	v_fmamk_f32 v83, v83, 0x3dd53b94, v215
	v_fmamk_f32 v84, v84, 0x3dd53b94, v215
	v_fmamk_f32 v85, v85, 0x3dd53b94, v215
	v_fmamk_f32 v86, v86, 0x3dd53b94, v215
	v_fmamk_f32 v87, v87, 0x3dd53b94, v215
	v_fmamk_f32 v88, v88, 0x3dd53b94, v215
	v_fmamk_f32 v89, v89, 0x3dd53b94, v215
	v_fmamk_f32 v90, v90, 0x3dd53b94, v215
	v_fmamk_f32 v91, v91, 0x3dd53b94, v215
	v_fmamk_f32 v92, v92, 0x3dd53b94, v215
	v_fmamk_f32 v93, v93, 0x3dd53b94, v215
	v_fmamk_f32 v94, v94, 0x3dd53b94, v215
	v_fmamk_f32 v95, v95, 0x3dd53b94, v215
	v_exp_f32_e32 v148, v80
	v_exp_f32_e32 v163, v81
	v_exp_f32_e32 v149, v82
	v_exp_f32_e32 v162, v83
	v_exp_f32_e32 v150, v84
	v_exp_f32_e32 v161, v85
	v_exp_f32_e32 v151, v86
	v_exp_f32_e32 v160, v87
	v_exp_f32_e32 v152, v88
	v_exp_f32_e32 v159, v89
	v_exp_f32_e32 v153, v90
	v_exp_f32_e32 v158, v91
	v_exp_f32_e32 v154, v92
	v_exp_f32_e32 v157, v93
	v_exp_f32_e32 v155, v94
	v_exp_f32_e32 v156, v95
	v_fmamk_f32 v224, v64, 0x3dd53b94, v215
	v_fmamk_f32 v225, v65, 0x3dd53b94, v215
	v_fmamk_f32 v226, v66, 0x3dd53b94, v215
	v_fmamk_f32 v227, v67, 0x3dd53b94, v215
	v_fmamk_f32 v228, v68, 0x3dd53b94, v215
	v_fmamk_f32 v217, v69, 0x3dd53b94, v215
	v_fmamk_f32 v218, v70, 0x3dd53b94, v215
	v_fmamk_f32 v219, v71, 0x3dd53b94, v215
	v_fmamk_f32 v220, v72, 0x3dd53b94, v215
	v_fmamk_f32 v221, v73, 0x3dd53b94, v215
	v_fmamk_f32 v222, v74, 0x3dd53b94, v215
	v_fmamk_f32 v223, v75, 0x3dd53b94, v215
	v_fmamk_f32 v216, v76, 0x3dd53b94, v215
	v_fmamk_f32 v229, v77, 0x3dd53b94, v215
	v_fmamk_f32 v230, v78, 0x3dd53b94, v215
	v_fmac_f32_e32 v215, 0x3dd53b94, v79
	s_barrier
	s_waitcnt vmcnt(0)
	ds_write_b128 v205, v[128:131] offset:49152
	ds_write_b128 v206, v[132:135] offset:49152
	s_cbranch_vccz .LBB0_977
	s_and_saveexec_b64 s[0:1], s[2:3]
	ds_write_b32 v201, v213 offset:128
	s_or_b64 exec, exec, s[0:1]
	s_waitcnt lgkmcnt(0)
	ds_read_b128 v[232:235], v175 offset:224
	ds_read_b128 v[236:239], v175 offset:192
	ds_read_b128 v[240:243], v175 offset:160
	ds_read_b128 v[244:247], v175 offset:128
	s_waitcnt lgkmcnt(3)
	v_pk_mul_f32 v[62:63], v[62:63], v[234:235]
	s_waitcnt lgkmcnt(2)
	v_pk_mul_f32 v[58:59], v[58:59], v[238:239]
	s_waitcnt lgkmcnt(1)
	v_pk_mul_f32 v[54:55], v[54:55], v[242:243]
	s_waitcnt lgkmcnt(0)
	v_pk_mul_f32 v[50:51], v[50:51], v[246:247]
	v_pk_mul_f32 v[60:61], v[60:61], v[232:233]
	v_pk_mul_f32 v[56:57], v[56:57], v[236:237]
	v_pk_mul_f32 v[52:53], v[52:53], v[240:241]
	v_pk_mul_f32 v[48:49], v[48:49], v[244:245]
	v_pk_mul_f32 v[46:47], v[46:47], v[234:235]
	v_pk_mul_f32 v[42:43], v[42:43], v[238:239]
	v_pk_mul_f32 v[38:39], v[38:39], v[242:243]
	v_pk_mul_f32 v[34:35], v[34:35], v[246:247]
	v_pk_mul_f32 v[44:45], v[44:45], v[232:233]
	v_pk_mul_f32 v[40:41], v[40:41], v[236:237]
	v_pk_mul_f32 v[36:37], v[36:37], v[240:241]
	v_pk_mul_f32 v[32:33], v[32:33], v[244:245]
	v_pk_mul_f32 v[30:31], v[30:31], v[234:235]
	v_pk_mul_f32 v[26:27], v[26:27], v[238:239]
	v_pk_mul_f32 v[22:23], v[22:23], v[242:243]
	v_pk_mul_f32 v[18:19], v[18:19], v[246:247]
	v_pk_mul_f32 v[28:29], v[28:29], v[232:233]
	v_pk_mul_f32 v[24:25], v[24:25], v[236:237]
	v_pk_mul_f32 v[20:21], v[20:21], v[240:241]
	v_pk_mul_f32 v[16:17], v[16:17], v[244:245]
	v_pk_mul_f32 v[14:15], v[14:15], v[234:235]
	v_pk_mul_f32 v[10:11], v[10:11], v[238:239]
	v_pk_mul_f32 v[6:7], v[6:7], v[242:243]
	v_pk_mul_f32 v[2:3], v[2:3], v[246:247]
	v_pk_mul_f32 v[12:13], v[12:13], v[232:233]
	v_pk_mul_f32 v[8:9], v[8:9], v[236:237]
	v_pk_mul_f32 v[4:5], v[4:5], v[240:241]
	v_pk_mul_f32 v[0:1], v[0:1], v[244:245]
; __device__ __forceinline__ void finishSM(f32x16& p0, f32x16& p1, float alpha, float& l_reg, bf16x8& pa0, bf16x8& pa1, bf16x8& pa2, bf16x8& pa3) {
; #pragma unroll
;     for (int r = 0; r < 16; ++r) p1[r] = __builtin_amdgcn_exp2f(p1[r]);
;     float ps = 0;
; #pragma unroll
;     for (int r = 0; r < 16; ++r) ps += p0[r];
; #pragma unroll
;     for (int r = 0; r < 16; ++r) ps += p1[r];
;     { auto rr = __builtin_amdgcn_permlane32_swap(__float_as_uint(ps), __float_as_uint(ps), false, false);
;       ps = __uint_as_float(rr[0]) + __uint_as_float(rr[1]); }
;     l_reg = l_reg * alpha + ps;
;     PK4(p0, 0, pa0); PK4(p0, 8, pa1); PK4(p1, 0, pa2); PK4(p1, 8, pa3);
; }
; template <int KB>
; __device__ __forceinline__ void qkt(f32x16& p0, f32x16& p1, const char* K_lds, int r32, int hi, const bf16x8* qr, const char* qx) {
;     p0 = f32x16{}; p1 = f32x16{};
;     const char* kb[4];
; #pragma unroll
;     for (int dd = 0; dd < 4; ++dd) kb[dd] = K_lds + KB * SHM_K + KSWZ(r32, (dd * 16 + hi * 8) * 2);
; #pragma unroll
;     for (int d0 = 0; d0 < 12; ++d0) { const char* a = kb[d0 & 3] + (d0 >> 2) * 128;
;         bf16x8 b0 = *reinterpret_cast<const bf16x8*>(a);
;         bf16x8 b1 = *reinterpret_cast<const bf16x8*>(a + 32 * 384);
;         const bf16x8 q = d0 < 8 ? qr[d0 & 7] : *reinterpret_cast<const bf16x8*>(qx + (d0 - 8) * 1024);
;         p0 = __builtin_amdgcn_mfma_f32_32x32x16_bf16(b0, q, p0, 0, 0, 0);
;         p1 = __builtin_amdgcn_mfma_f32_32x32x16_bf16(b1, q, p1, 0, 0, 0); }
.LBB0_977:
	s_waitcnt lgkmcnt(0)
	s_barrier
	ds_read_b128 v[128:131], v194
	ds_read_b128 v[132:135], v194 offset:12288
	ds_read_b128 v[136:139], v195
	ds_read_b128 v[140:143], v195 offset:12288
	ds_read_b128 v[144:147], v196
	ds_read_b128 v[236:239], v196 offset:12288
	v_exp_f32_e32 v224, v224
	v_exp_f32_e32 v225, v225
	s_nop 1
	v_exp_f32_e32 v226, v226
	s_waitcnt lgkmcnt(5)
	v_mfma_f32_32x32x16_bf16 v[80:95], v[128:131], v[124:127], 0
	v_exp_f32_e32 v227, v227
	v_exp_f32_e32 v228, v228
	v_exp_f32_e32 v217, v217
	s_waitcnt lgkmcnt(4)
	v_mfma_f32_32x32x16_bf16 v[64:79], v[132:135], v[124:127], 0
	ds_read_b128 v[128:131], v197
	ds_read_b128 v[132:135], v197 offset:12288
	v_exp_f32_e32 v218, v218
	v_exp_f32_e32 v219, v219
	v_exp_f32_e32 v220, v220
	s_waitcnt lgkmcnt(5)
	v_mfma_f32_32x32x16_bf16 v[80:95], v[136:139], v[120:123], v[80:95]
	v_exp_f32_e32 v221, v221
	v_exp_f32_e32 v222, v222
	v_exp_f32_e32 v223, v223
	s_waitcnt lgkmcnt(4)
	v_mfma_f32_32x32x16_bf16 v[64:79], v[140:143], v[120:123], v[64:79]
	ds_read_b128 v[136:139], v194 offset:128
	ds_read_b128 v[140:143], v194 offset:12416
	v_exp_f32_e32 v231, v216
	v_exp_f32_e32 v229, v229
	v_exp_f32_e32 v230, v230
	s_waitcnt lgkmcnt(5)
	v_mfma_f32_32x32x16_bf16 v[80:95], v[144:147], v[116:119], v[80:95]
	v_exp_f32_e32 v232, v215
	v_add_f32_e32 v215, 0, v148
	v_add_f32_e32 v215, v163, v215
	s_waitcnt lgkmcnt(4)
	v_mfma_f32_32x32x16_bf16 v[64:79], v[236:239], v[116:119], v[64:79]
	ds_read_b128 v[144:147], v195 offset:128
	ds_read_b128 v[236:239], v195 offset:12416
	v_add_f32_e32 v215, v149, v215
	v_add_f32_e32 v215, v162, v215
	v_add_f32_e32 v215, v150, v215
	s_waitcnt lgkmcnt(5)
	v_mfma_f32_32x32x16_bf16 v[80:95], v[128:131], v[112:115], v[80:95]
	v_add_f32_e32 v215, v161, v215
	v_add_f32_e32 v215, v151, v215
	v_add_f32_e32 v215, v160, v215
	s_waitcnt lgkmcnt(4)
	v_mfma_f32_32x32x16_bf16 v[64:79], v[132:135], v[112:115], v[64:79]
	ds_read_b128 v[128:131], v196 offset:128
	ds_read_b128 v[132:135], v196 offset:12416
	v_add_f32_e32 v215, v152, v215
	v_add_f32_e32 v215, v159, v215
	v_add_f32_e32 v215, v153, v215
	s_waitcnt lgkmcnt(5)
	v_mfma_f32_32x32x16_bf16 v[80:95], v[136:139], v[108:111], v[80:95]
	v_add_f32_e32 v215, v158, v215
	v_add_f32_e32 v215, v154, v215
	v_add_f32_e32 v215, v157, v215
	s_waitcnt lgkmcnt(4)
	v_mfma_f32_32x32x16_bf16 v[64:79], v[140:143], v[108:111], v[64:79]
	ds_read_b128 v[136:139], v197 offset:128
	ds_read_b128 v[140:143], v197 offset:12416
	v_add_f32_e32 v215, v155, v215
	v_add_f32_e32 v215, v156, v215
	v_add_f32_e32 v215, v224, v215
	s_waitcnt lgkmcnt(5)
	v_mfma_f32_32x32x16_bf16 v[80:95], v[144:147], v[104:107], v[80:95]
	v_add_f32_e32 v215, v225, v215
	v_add_f32_e32 v215, v226, v215
	v_add_f32_e32 v215, v227, v215
	s_waitcnt lgkmcnt(4)
	v_mfma_f32_32x32x16_bf16 v[64:79], v[236:239], v[104:107], v[64:79]
	ds_read_b128 v[240:243], v204
	ds_read_b128 v[144:147], v194 offset:256
	ds_read_b128 v[236:239], v194 offset:12544
	v_add_f32_e32 v215, v228, v215
	v_add_f32_e32 v215, v217, v215
	v_add_f32_e32 v215, v218, v215
	s_waitcnt lgkmcnt(6)
	v_mfma_f32_32x32x16_bf16 v[80:95], v[128:131], v[100:103], v[80:95]
	v_add_f32_e32 v215, v219, v215
	v_add_f32_e32 v215, v220, v215
	v_add_f32_e32 v215, v221, v215
	s_waitcnt lgkmcnt(5)
	v_mfma_f32_32x32x16_bf16 v[64:79], v[132:135], v[100:103], v[64:79]
	ds_read_b128 v[244:247], v204 offset:1024
	ds_read_b128 v[128:131], v195 offset:256
	ds_read_b128 v[132:135], v195 offset:12544
	v_add_f32_e32 v215, v222, v215
	v_add_f32_e32 v215, v223, v215
	v_add_f32_e32 v215, v231, v215
	s_waitcnt lgkmcnt(7)
	v_mfma_f32_32x32x16_bf16 v[80:95], v[136:139], v[96:99], v[80:95]
	v_add_f32_e32 v215, v229, v215
	v_add_f32_e32 v215, v230, v215
	v_add_f32_e32 v215, v232, v215
	s_waitcnt lgkmcnt(6)
	v_mfma_f32_32x32x16_bf16 v[64:79], v[140:143], v[96:99], v[64:79]
	ds_read_b128 v[136:139], v196 offset:256
	ds_read_b128 v[140:143], v196 offset:12544
	v_mov_b32_e32 v216, v215
	v_cvt_pk_bf16_f32 v148, v148, v163
	v_cvt_pk_bf16_f32 v149, v149, v162
	s_waitcnt lgkmcnt(6)
	v_mfma_f32_32x32x16_bf16 v[80:95], v[144:147], v[240:243], v[80:95]
	v_cvt_pk_bf16_f32 v150, v150, v161
	v_cvt_pk_bf16_f32 v151, v151, v160
	v_cvt_pk_bf16_f32 v152, v152, v159
	s_waitcnt lgkmcnt(5)
	v_mfma_f32_32x32x16_bf16 v[64:79], v[236:239], v[240:243], v[64:79]
	ds_read_b128 v[144:147], v197 offset:256
	ds_read_b128 v[236:239], v197 offset:12544
	ds_read_b128 v[240:243], v204 offset:2048
	v_cvt_pk_bf16_f32 v153, v153, v158
	v_cvt_pk_bf16_f32 v154, v154, v157
	v_cvt_pk_bf16_f32 v155, v155, v156
	s_waitcnt lgkmcnt(6)
	v_mfma_f32_32x32x16_bf16 v[80:95], v[128:131], v[244:247], v[80:95]
	v_cvt_pk_bf16_f32 v156, v224, v225
	v_cvt_pk_bf16_f32 v157, v226, v227
	v_cvt_pk_bf16_f32 v158, v228, v217
	s_waitcnt lgkmcnt(5)
	v_mfma_f32_32x32x16_bf16 v[64:79], v[132:135], v[244:247], v[64:79]
	ds_read_b128 v[244:247], v204 offset:3072
	v_cvt_pk_bf16_f32 v159, v218, v219
	v_cvt_pk_bf16_f32 v160, v220, v221
	v_cvt_pk_bf16_f32 v161, v222, v223
	s_waitcnt lgkmcnt(1)
	v_mfma_f32_32x32x16_bf16 v[80:95], v[136:139], v[240:243], v[80:95]
	v_cvt_pk_bf16_f32 v162, v231, v229
	v_cvt_pk_bf16_f32 v163, v230, v232
	s_nop 1
	s_waitcnt lgkmcnt(4)
	v_mfma_f32_32x32x16_bf16 v[64:79], v[140:143], v[240:243], v[64:79]
	v_permlane32_swap_b32_e32 v215, v216
	v_permlane32_swap_b32_e32 v148, v150
	v_permlane32_swap_b32_e32 v149, v151
	s_waitcnt lgkmcnt(0)
	v_mfma_f32_32x32x16_bf16 v[80:95], v[144:147], v[244:247], v[80:95]
	v_permlane32_swap_b32_e32 v152, v154
	v_permlane32_swap_b32_e32 v153, v155
	v_permlane32_swap_b32_e32 v156, v158
	s_waitcnt lgkmcnt(2)
	v_mfma_f32_32x32x16_bf16 v[64:79], v[236:239], v[244:247], v[64:79]
	v_permlane32_swap_b32_e32 v157, v159
	v_permlane32_swap_b32_e32 v160, v162
	v_permlane32_swap_b32_e32 v161, v163
	s_add_i32 s0, s74, 1
	s_cmp_lt_i32 s0, s75
	s_cselect_b64 s[36:37], -1, 0
	s_cmp_ge_i32 s0, s75
	s_cbranch_scc1 .LBB0_979
	v_add_co_u32_e32 v128, vcc, 0xc0000, v180
	s_nop 1
	v_addc_co_u32_e32 v129, vcc, 0, v181, vcc
	v_add_co_u32_e32 v132, vcc, 0xe0000, v180
	s_nop 1
	v_addc_co_u32_e32 v133, vcc, 0, v181, vcc
	v_add_co_u32_e32 v136, vcc, 0xc0000, v178
	s_nop 1
	v_addc_co_u32_e32 v137, vcc, 0, v179, vcc
	v_add_co_u32_e32 v140, vcc, 0xe0000, v178
	s_nop 1
	v_addc_co_u32_e32 v141, vcc, 0, v179, vcc
	v_add_co_u32_e32 v144, vcc, 0x2000, v176
	s_nop 1
	v_addc_co_u32_e32 v145, vcc, 0, v177, vcc
	global_load_dwordx4 v[136:139], v[136:137], off
	global_load_dwordx4 v[140:143], v[140:141], off
	global_load_dwordx4 v[144:147], v[144:145], off
	global_load_dwordx4 v[128:131], v[128:129], off
	global_load_dwordx4 v[132:135], v[132:133], off
